# speedup vs baseline: 1.0046x; 1.0046x over previous
; __device__ __forceinline__ void topk_row(const Params& p, int r, int lane, __attribute__((address_space(3))) int* out) {
;     ...
;     const int t = r & (L - 1), n = t + 1;
;     const float* sc = p.SC + (size_t)r * L;
;     const int nch = (n + 63) >> 6;
;     int lo = lane;
;     asm volatile("" : "+v"(lo));
;     unsigned key[128];
;     const float* scl = sc + lo;
; #pragma unroll
;     for (int i = 0; i < 128; ++i) {
;       const int ic = min(i, nch - 1);
;       key[i] = __float_as_uint(scl[ic * 64]);
;     }
.LBB0_71:
	s_andn2_b64 vcc, exec, s[0:1]
	s_cbranch_vccnz .LBB0_902
	v_readlane_b32 s0, v244, 0
	v_readlane_b32 s1, v244, 1
	s_ashr_i32 s1, s0, 31
	v_writelane_b32 v244, s0, 0
	v_readlane_b32 s16, v246, 0
	v_readlane_b32 s18, v246, 2
	v_writelane_b32 v244, s1, 1
	s_lshl_b64 s[0:1], s[0:1], 15
	v_readlane_b32 s19, v246, 3
	s_add_u32 s0, s18, s0
	s_addc_u32 s1, s19, s1
	s_add_i32 s4, s15, 64
	v_mov_b32_e32 v0, v218
	s_waitcnt lgkmcnt(0)
	s_lshr_b32 s4, s4, 6
	v_readlane_b32 s17, v246, 1
	v_ashrrev_i32_e32 v1, 31, v0
	v_lshl_add_u64 v[2:3], v[0:1], 2, s[0:1]
	s_add_i32 s0, s4, -1
	s_min_u32 s1, s0, 5
	s_lshl_b32 s4, s1, 8
	s_min_u32 s1, s0, 6
	v_lshl_add_u64 v[10:11], v[2:3], 0, s[4:5]
	s_lshl_b32 s4, s1, 8
	s_min_u32 s1, s0, 7
	global_load_dword v9, v[2:3], off nt
	global_load_dword v8, v[2:3], off offset:256 nt
	global_load_dword v7, v[2:3], off offset:512 nt
	global_load_dword v4, v[2:3], off offset:768 nt
	global_load_dword v1, v[2:3], off offset:1024 nt
	global_load_dword v5, v[10:11], off nt
	v_lshl_add_u64 v[10:11], v[2:3], 0, s[4:5]
	s_lshl_b32 s4, s1, 8
	s_min_u32 s1, s0, 8
	global_load_dword v6, v[10:11], off nt
	v_lshl_add_u64 v[10:11], v[2:3], 0, s[4:5]
	s_lshl_b32 s4, s1, 8
	s_min_u32 s1, s0, 9
	v_lshl_add_u64 v[12:13], v[2:3], 0, s[4:5]
	s_lshl_b32 s4, s1, 8
	s_min_u32 s1, s0, 10
	global_load_dword v11, v[10:11], off nt
	s_nop 0
	global_load_dword v10, v[12:13], off nt
	v_lshl_add_u64 v[12:13], v[2:3], 0, s[4:5]
	s_lshl_b32 s4, s1, 8
	s_min_u32 s1, s0, 11
	v_lshl_add_u64 v[14:15], v[2:3], 0, s[4:5]
	s_lshl_b32 s4, s1, 8
	s_min_u32 s1, s0, 12
	global_load_dword v12, v[12:13], off nt
	s_nop 0
	global_load_dword v13, v[14:15], off nt
	v_lshl_add_u64 v[14:15], v[2:3], 0, s[4:5]
	s_lshl_b32 s4, s1, 8
	s_min_u32 s1, s0, 13
	v_lshl_add_u64 v[16:17], v[2:3], 0, s[4:5]
	s_lshl_b32 s4, s1, 8
	s_min_u32 s1, s0, 14
	global_load_dword v14, v[14:15], off nt
	s_nop 0
	global_load_dword v15, v[16:17], off nt
	v_lshl_add_u64 v[16:17], v[2:3], 0, s[4:5]
	s_lshl_b32 s4, s1, 8
	s_min_u32 s1, s0, 15
	v_lshl_add_u64 v[18:19], v[2:3], 0, s[4:5]
	s_lshl_b32 s4, s1, 8
	s_min_u32 s1, s0, 16
	global_load_dword v16, v[16:17], off nt
	s_nop 0
	global_load_dword v17, v[18:19], off nt
	v_lshl_add_u64 v[18:19], v[2:3], 0, s[4:5]
	s_lshl_b32 s4, s1, 8
	s_min_u32 s1, s0, 17
	v_lshl_add_u64 v[20:21], v[2:3], 0, s[4:5]
	s_lshl_b32 s4, s1, 8
	s_min_u32 s1, s0, 18
	global_load_dword v19, v[18:19], off nt
	s_nop 0
	global_load_dword v18, v[20:21], off nt
	v_lshl_add_u64 v[20:21], v[2:3], 0, s[4:5]
	s_lshl_b32 s4, s1, 8
	s_min_u32 s1, s0, 19
	v_lshl_add_u64 v[22:23], v[2:3], 0, s[4:5]
	s_lshl_b32 s4, s1, 8
	s_min_u32 s1, s0, 20
	global_load_dword v20, v[20:21], off nt
	s_nop 0
	global_load_dword v21, v[22:23], off nt
	v_lshl_add_u64 v[22:23], v[2:3], 0, s[4:5]
	s_lshl_b32 s4, s1, 8
	s_min_u32 s1, s0, 21
	v_lshl_add_u64 v[24:25], v[2:3], 0, s[4:5]
	s_lshl_b32 s4, s1, 8
	s_min_u32 s1, s0, 22
	global_load_dword v22, v[22:23], off nt
	s_nop 0
	global_load_dword v23, v[24:25], off nt
	v_lshl_add_u64 v[24:25], v[2:3], 0, s[4:5]
	s_lshl_b32 s4, s1, 8
	s_min_u32 s1, s0, 23
	v_lshl_add_u64 v[26:27], v[2:3], 0, s[4:5]
	s_lshl_b32 s4, s1, 8
	s_min_u32 s1, s0, 24
	global_load_dword v24, v[24:25], off nt
	s_nop 0
	global_load_dword v25, v[26:27], off nt
	v_lshl_add_u64 v[26:27], v[2:3], 0, s[4:5]
	s_lshl_b32 s4, s1, 8
	s_min_u32 s1, s0, 25
	v_lshl_add_u64 v[28:29], v[2:3], 0, s[4:5]
	s_lshl_b32 s4, s1, 8
	s_min_u32 s1, s0, 26
	global_load_dword v27, v[26:27], off nt
	s_nop 0
	global_load_dword v26, v[28:29], off nt
	v_lshl_add_u64 v[28:29], v[2:3], 0, s[4:5]
	s_lshl_b32 s4, s1, 8
	s_min_u32 s1, s0, 27
	v_lshl_add_u64 v[30:31], v[2:3], 0, s[4:5]
	s_lshl_b32 s4, s1, 8
	s_min_u32 s1, s0, 28
	global_load_dword v28, v[28:29], off nt
	s_nop 0
	global_load_dword v29, v[30:31], off nt
	v_lshl_add_u64 v[30:31], v[2:3], 0, s[4:5]
	s_lshl_b32 s4, s1, 8
	s_min_u32 s1, s0, 29
	v_lshl_add_u64 v[34:35], v[2:3], 0, s[4:5]
	s_lshl_b32 s4, s1, 8
	s_min_u32 s1, s0, 30
	global_load_dword v30, v[30:31], off nt
	s_nop 0
	global_load_dword v31, v[34:35], off nt
	v_lshl_add_u64 v[34:35], v[2:3], 0, s[4:5]
	s_lshl_b32 s4, s1, 8
	s_min_u32 s1, s0, 31
	global_load_dword v32, v[34:35], off nt
	v_lshl_add_u64 v[34:35], v[2:3], 0, s[4:5]
	s_lshl_b32 s4, s1, 8
	s_min_u32 s1, s0, 32
	v_lshl_add_u64 v[36:37], v[2:3], 0, s[4:5]
	s_lshl_b32 s4, s1, 8
	s_min_u32 s1, s0, 33
	v_lshl_add_u64 v[38:39], v[2:3], 0, s[4:5]
	s_lshl_b32 s4, s1, 8
	s_min_u32 s1, s0, 34
	global_load_dword v34, v[34:35], off nt
	s_nop 0
	global_load_dword v36, v[36:37], off nt
	s_nop 0
	global_load_dword v35, v[38:39], off nt
	v_lshl_add_u64 v[38:39], v[2:3], 0, s[4:5]
	s_lshl_b32 s4, s1, 8
	s_min_u32 s1, s0, 35
	global_load_dword v37, v[38:39], off nt
	v_lshl_add_u64 v[38:39], v[2:3], 0, s[4:5]
	s_lshl_b32 s4, s1, 8
	s_min_u32 s1, s0, 36
	v_lshl_add_u64 v[40:41], v[2:3], 0, s[4:5]
	s_lshl_b32 s4, s1, 8
	s_min_u32 s1, s0, 37
	global_load_dword v38, v[38:39], off nt
	s_nop 0
	global_load_dword v39, v[40:41], off nt
	v_lshl_add_u64 v[40:41], v[2:3], 0, s[4:5]
	s_lshl_b32 s4, s1, 8
	s_min_u32 s1, s0, 38
	v_lshl_add_u64 v[42:43], v[2:3], 0, s[4:5]
	s_lshl_b32 s4, s1, 8
	s_min_u32 s1, s0, 39
	global_load_dword v40, v[40:41], off nt
	s_nop 0
	global_load_dword v41, v[42:43], off nt
	v_lshl_add_u64 v[42:43], v[2:3], 0, s[4:5]
	s_lshl_b32 s4, s1, 8
	s_min_u32 s1, s0, 40
	v_lshl_add_u64 v[44:45], v[2:3], 0, s[4:5]
	s_lshl_b32 s4, s1, 8
	s_min_u32 s1, s0, 41
	v_lshl_add_u64 v[46:47], v[2:3], 0, s[4:5]
	s_lshl_b32 s4, s1, 8
	s_min_u32 s1, s0, 42
	global_load_dword v42, v[42:43], off nt
	s_nop 0
	global_load_dword v44, v[44:45], off nt
	s_nop 0
; __device__ __forceinline__ void topk_row(const Params& p, int r, int lane, __attribute__((address_space(3))) int* out) {
;     ...
;     for (int i = 0; i < 128; ++i) {
;       const int ic = min(i, nch - 1);
;       key[i] = __float_as_uint(scl[ic * 64]);
;     }
	global_load_dword v43, v[46:47], off nt
	v_lshl_add_u64 v[46:47], v[2:3], 0, s[4:5]
	s_lshl_b32 s4, s1, 8
	s_min_u32 s1, s0, 43
	global_load_dword v45, v[46:47], off nt
	v_lshl_add_u64 v[46:47], v[2:3], 0, s[4:5]
	s_lshl_b32 s4, s1, 8
	s_min_u32 s1, s0, 44
	v_lshl_add_u64 v[48:49], v[2:3], 0, s[4:5]
	s_lshl_b32 s4, s1, 8
	s_min_u32 s1, s0, 45
	global_load_dword v46, v[46:47], off nt
	s_nop 0
	global_load_dword v47, v[48:49], off nt
	v_lshl_add_u64 v[48:49], v[2:3], 0, s[4:5]
	s_lshl_b32 s4, s1, 8
	s_min_u32 s1, s0, 46
	v_lshl_add_u64 v[50:51], v[2:3], 0, s[4:5]
	s_lshl_b32 s4, s1, 8
	s_min_u32 s1, s0, 47
	global_load_dword v48, v[48:49], off nt
	s_nop 0
	global_load_dword v49, v[50:51], off nt
	v_lshl_add_u64 v[50:51], v[2:3], 0, s[4:5]
	s_lshl_b32 s4, s1, 8
	s_min_u32 s1, s0, 48
	v_lshl_add_u64 v[52:53], v[2:3], 0, s[4:5]
	s_lshl_b32 s4, s1, 8
	s_min_u32 s1, s0, 49
	v_lshl_add_u64 v[54:55], v[2:3], 0, s[4:5]
	s_lshl_b32 s4, s1, 8
	s_min_u32 s1, s0, 50
	global_load_dword v50, v[50:51], off nt
	s_nop 0
	global_load_dword v52, v[52:53], off nt
	s_nop 0
	global_load_dword v51, v[54:55], off nt
	v_lshl_add_u64 v[54:55], v[2:3], 0, s[4:5]
	s_lshl_b32 s4, s1, 8
	s_min_u32 s1, s0, 51
	global_load_dword v53, v[54:55], off nt
	v_lshl_add_u64 v[54:55], v[2:3], 0, s[4:5]
	s_lshl_b32 s4, s1, 8
	s_min_u32 s1, s0, 52
	v_lshl_add_u64 v[56:57], v[2:3], 0, s[4:5]
	s_lshl_b32 s4, s1, 8
	s_min_u32 s1, s0, 53
	global_load_dword v54, v[54:55], off nt
	s_nop 0
	global_load_dword v55, v[56:57], off nt
	v_lshl_add_u64 v[56:57], v[2:3], 0, s[4:5]
	s_lshl_b32 s4, s1, 8
	s_min_u32 s1, s0, 54
	v_lshl_add_u64 v[58:59], v[2:3], 0, s[4:5]
	s_lshl_b32 s4, s1, 8
	s_min_u32 s1, s0, 55
	global_load_dword v56, v[56:57], off nt
	s_nop 0
	global_load_dword v57, v[58:59], off nt
	v_lshl_add_u64 v[58:59], v[2:3], 0, s[4:5]
	s_lshl_b32 s4, s1, 8
	s_min_u32 s1, s0, 56
	v_lshl_add_u64 v[60:61], v[2:3], 0, s[4:5]
	s_lshl_b32 s4, s1, 8
	s_min_u32 s1, s0, 57
	v_lshl_add_u64 v[62:63], v[2:3], 0, s[4:5]
	s_lshl_b32 s4, s1, 8
	s_min_u32 s1, s0, 58
	global_load_dword v58, v[58:59], off nt
	s_nop 0
	global_load_dword v60, v[60:61], off nt
	s_nop 0
	global_load_dword v59, v[62:63], off nt
	v_lshl_add_u64 v[62:63], v[2:3], 0, s[4:5]
	s_lshl_b32 s4, s1, 8
	s_min_u32 s1, s0, 59
	global_load_dword v61, v[62:63], off nt
	v_lshl_add_u64 v[62:63], v[2:3], 0, s[4:5]
	s_lshl_b32 s4, s1, 8
	s_min_u32 s1, s0, 60
	v_lshl_add_u64 v[64:65], v[2:3], 0, s[4:5]
	s_lshl_b32 s4, s1, 8
	s_min_u32 s1, s0, 61
	global_load_dword v62, v[62:63], off nt
	s_nop 0
	global_load_dword v63, v[64:65], off nt
	v_lshl_add_u64 v[64:65], v[2:3], 0, s[4:5]
	s_lshl_b32 s4, s1, 8
	s_min_u32 s1, s0, 62
	v_lshl_add_u64 v[66:67], v[2:3], 0, s[4:5]
	s_lshl_b32 s4, s1, 8
	s_min_u32 s1, s0, 63
	global_load_dword v64, v[64:65], off nt
	s_nop 0
	global_load_dword v65, v[66:67], off nt
	v_lshl_add_u64 v[66:67], v[2:3], 0, s[4:5]
	s_lshl_b32 s4, s1, 8
	s_min_u32 s1, s0, 64
	v_lshl_add_u64 v[68:69], v[2:3], 0, s[4:5]
	s_lshl_b32 s4, s1, 8
	s_min_u32 s1, s0, 0x41
	global_load_dword v66, v[66:67], off nt
	s_nop 0
	global_load_dword v67, v[68:69], off nt
	v_lshl_add_u64 v[68:69], v[2:3], 0, s[4:5]
	s_lshl_b32 s4, s1, 8
	s_min_u32 s1, s0, 0x42
	global_load_dword v115, v[68:69], off nt
	v_lshl_add_u64 v[68:69], v[2:3], 0, s[4:5]
	s_lshl_b32 s4, s1, 8
	s_min_u32 s1, s0, 0x43
	global_load_dword v116, v[68:69], off nt
	v_lshl_add_u64 v[68:69], v[2:3], 0, s[4:5]
	s_lshl_b32 s4, s1, 8
	s_min_u32 s1, s0, 0x44
	global_load_dword v117, v[68:69], off nt
	v_lshl_add_u64 v[68:69], v[2:3], 0, s[4:5]
	s_lshl_b32 s4, s1, 8
	s_min_u32 s1, s0, 0x45
	global_load_dword v118, v[68:69], off nt
	v_lshl_add_u64 v[68:69], v[2:3], 0, s[4:5]
	s_lshl_b32 s4, s1, 8
	s_min_u32 s1, s0, 0x46
	global_load_dword v119, v[68:69], off nt
	v_lshl_add_u64 v[68:69], v[2:3], 0, s[4:5]
	s_lshl_b32 s4, s1, 8
	s_min_u32 s1, s0, 0x47
	global_load_dword v120, v[68:69], off nt
	v_lshl_add_u64 v[68:69], v[2:3], 0, s[4:5]
	s_lshl_b32 s4, s1, 8
	s_min_u32 s1, s0, 0x48
	global_load_dword v121, v[68:69], off nt
	v_lshl_add_u64 v[68:69], v[2:3], 0, s[4:5]
	s_lshl_b32 s4, s1, 8
	s_min_u32 s1, s0, 0x49
	global_load_dword v123, v[68:69], off nt
	v_lshl_add_u64 v[68:69], v[2:3], 0, s[4:5]
	s_lshl_b32 s4, s1, 8
	s_min_u32 s1, s0, 0x4a
	global_load_dword v122, v[68:69], off nt
	v_lshl_add_u64 v[68:69], v[2:3], 0, s[4:5]
	s_lshl_b32 s4, s1, 8
	s_min_u32 s1, s0, 0x4b
	global_load_dword v140, v[68:69], off nt
	v_lshl_add_u64 v[68:69], v[2:3], 0, s[4:5]
	s_lshl_b32 s4, s1, 8
	s_min_u32 s1, s0, 0x4c
	global_load_dword v141, v[68:69], off nt
	v_lshl_add_u64 v[68:69], v[2:3], 0, s[4:5]
	s_lshl_b32 s4, s1, 8
	s_min_u32 s1, s0, 0x4d
	global_load_dword v142, v[68:69], off nt
	v_lshl_add_u64 v[68:69], v[2:3], 0, s[4:5]
	s_lshl_b32 s4, s1, 8
	s_min_u32 s1, s0, 0x4e
	global_load_dword v143, v[68:69], off nt
	v_lshl_add_u64 v[68:69], v[2:3], 0, s[4:5]
	s_lshl_b32 s4, s1, 8
	s_min_u32 s1, s0, 0x4f
	global_load_dword v144, v[68:69], off nt
	v_lshl_add_u64 v[68:69], v[2:3], 0, s[4:5]
	s_lshl_b32 s4, s1, 8
	s_min_u32 s1, s0, 0x50
	global_load_dword v145, v[68:69], off nt
	v_lshl_add_u64 v[68:69], v[2:3], 0, s[4:5]
	s_lshl_b32 s4, s1, 8
	s_min_u32 s1, s0, 0x51
	global_load_dword v147, v[68:69], off nt
	v_lshl_add_u64 v[68:69], v[2:3], 0, s[4:5]
	s_lshl_b32 s4, s1, 8
	s_min_u32 s1, s0, 0x52
	global_load_dword v146, v[68:69], off nt
	v_lshl_add_u64 v[68:69], v[2:3], 0, s[4:5]
	s_lshl_b32 s4, s1, 8
	s_min_u32 s1, s0, 0x53
	global_load_dword v148, v[68:69], off nt
	v_lshl_add_u64 v[68:69], v[2:3], 0, s[4:5]
	s_lshl_b32 s4, s1, 8
	s_min_u32 s1, s0, 0x54
	global_load_dword v149, v[68:69], off nt
	v_lshl_add_u64 v[68:69], v[2:3], 0, s[4:5]
; __device__ __forceinline__ void topk_row(const Params& p, int r, int lane, __attribute__((address_space(3))) int* out) {
;     ...
;     for (int i = 0; i < 128; ++i) {
;       const int ic = min(i, nch - 1);
;       key[i] = __float_as_uint(scl[ic * 64]);
;     }
	s_lshl_b32 s4, s1, 8
	s_min_u32 s1, s0, 0x55
	global_load_dword v150, v[68:69], off nt
	v_lshl_add_u64 v[68:69], v[2:3], 0, s[4:5]
	s_lshl_b32 s4, s1, 8
	s_min_u32 s1, s0, 0x56
	global_load_dword v151, v[68:69], off nt
	v_lshl_add_u64 v[68:69], v[2:3], 0, s[4:5]
	s_lshl_b32 s4, s1, 8
	s_min_u32 s1, s0, 0x57
	global_load_dword v152, v[68:69], off nt
	v_lshl_add_u64 v[68:69], v[2:3], 0, s[4:5]
	s_lshl_b32 s4, s1, 8
	s_min_u32 s1, s0, 0x58
	global_load_dword v153, v[68:69], off nt
	v_lshl_add_u64 v[68:69], v[2:3], 0, s[4:5]
	s_lshl_b32 s4, s1, 8
	s_min_u32 s1, s0, 0x59
	global_load_dword v155, v[68:69], off nt
	v_lshl_add_u64 v[68:69], v[2:3], 0, s[4:5]
	s_lshl_b32 s4, s1, 8
	s_min_u32 s1, s0, 0x5a
	global_load_dword v154, v[68:69], off nt
	v_lshl_add_u64 v[68:69], v[2:3], 0, s[4:5]
	s_lshl_b32 s4, s1, 8
	s_min_u32 s1, s0, 0x5b
	global_load_dword v156, v[68:69], off nt
	v_lshl_add_u64 v[68:69], v[2:3], 0, s[4:5]
	s_lshl_b32 s4, s1, 8
	s_min_u32 s1, s0, 0x5c
	global_load_dword v157, v[68:69], off nt
	v_lshl_add_u64 v[68:69], v[2:3], 0, s[4:5]
	s_lshl_b32 s4, s1, 8
	s_min_u32 s1, s0, 0x5d
	global_load_dword v158, v[68:69], off nt
	v_lshl_add_u64 v[68:69], v[2:3], 0, s[4:5]
	s_lshl_b32 s4, s1, 8
	s_min_u32 s1, s0, 0x5e
	global_load_dword v159, v[68:69], off nt
	v_lshl_add_u64 v[68:69], v[2:3], 0, s[4:5]
	s_lshl_b32 s4, s1, 8
	s_min_u32 s1, s0, 0x5f
	global_load_dword v160, v[68:69], off nt
	v_lshl_add_u64 v[68:69], v[2:3], 0, s[4:5]
	s_lshl_b32 s4, s1, 8
	s_min_u32 s1, s0, 0x60
	global_load_dword v161, v[68:69], off nt
	v_lshl_add_u64 v[68:69], v[2:3], 0, s[4:5]
	s_lshl_b32 s4, s1, 8
	s_min_u32 s1, s0, 0x61
	global_load_dword v163, v[68:69], off nt
	v_lshl_add_u64 v[68:69], v[2:3], 0, s[4:5]
	s_lshl_b32 s4, s1, 8
	s_min_u32 s1, s0, 0x62
	global_load_dword v162, v[68:69], off nt
	v_lshl_add_u64 v[68:69], v[2:3], 0, s[4:5]
	s_lshl_b32 s4, s1, 8
	s_min_u32 s1, s0, 0x63
	global_load_dword v164, v[68:69], off nt
	v_lshl_add_u64 v[68:69], v[2:3], 0, s[4:5]
	s_lshl_b32 s4, s1, 8
	s_min_u32 s1, s0, 0x64
	global_load_dword v165, v[68:69], off nt
	v_lshl_add_u64 v[68:69], v[2:3], 0, s[4:5]
	s_lshl_b32 s4, s1, 8
	s_min_u32 s1, s0, 0x65
	global_load_dword v166, v[68:69], off nt
	v_lshl_add_u64 v[68:69], v[2:3], 0, s[4:5]
	s_lshl_b32 s4, s1, 8
	s_min_u32 s1, s0, 0x66
	global_load_dword v167, v[68:69], off nt
	v_lshl_add_u64 v[68:69], v[2:3], 0, s[4:5]
	s_lshl_b32 s4, s1, 8
	s_min_u32 s1, s0, 0x67
	global_load_dword v168, v[68:69], off nt
	v_lshl_add_u64 v[68:69], v[2:3], 0, s[4:5]
	s_lshl_b32 s4, s1, 8
	s_min_u32 s1, s0, 0x68
	global_load_dword v169, v[68:69], off nt
	v_lshl_add_u64 v[68:69], v[2:3], 0, s[4:5]
	s_lshl_b32 s4, s1, 8
	s_min_u32 s1, s0, 0x69
	global_load_dword v171, v[68:69], off nt
	v_lshl_add_u64 v[68:69], v[2:3], 0, s[4:5]
	s_lshl_b32 s4, s1, 8
	s_min_u32 s1, s0, 0x6a
	global_load_dword v170, v[68:69], off nt
	v_lshl_add_u64 v[68:69], v[2:3], 0, s[4:5]
	s_lshl_b32 s4, s1, 8
	s_min_u32 s1, s0, 0x6b
	global_load_dword v172, v[68:69], off nt
	v_lshl_add_u64 v[68:69], v[2:3], 0, s[4:5]
	s_lshl_b32 s4, s1, 8
	s_min_u32 s1, s0, 0x6c
	global_load_dword v173, v[68:69], off nt
	v_lshl_add_u64 v[68:69], v[2:3], 0, s[4:5]
	s_lshl_b32 s4, s1, 8
	s_min_u32 s1, s0, 0x6d
	global_load_dword v174, v[68:69], off nt
	v_lshl_add_u64 v[68:69], v[2:3], 0, s[4:5]
	s_lshl_b32 s4, s1, 8
	s_min_u32 s1, s0, 0x6e
	global_load_dword v175, v[68:69], off nt
	v_lshl_add_u64 v[68:69], v[2:3], 0, s[4:5]
	s_lshl_b32 s4, s1, 8
	s_min_u32 s1, s0, 0x6f
	global_load_dword v176, v[68:69], off nt
	v_lshl_add_u64 v[68:69], v[2:3], 0, s[4:5]
	s_lshl_b32 s4, s1, 8
	s_min_u32 s1, s0, 0x70
	global_load_dword v177, v[68:69], off nt
	v_lshl_add_u64 v[68:69], v[2:3], 0, s[4:5]
	s_lshl_b32 s4, s1, 8
	s_min_u32 s1, s0, 0x71
	global_load_dword v179, v[68:69], off nt
	v_lshl_add_u64 v[68:69], v[2:3], 0, s[4:5]
	s_lshl_b32 s4, s1, 8
	s_min_u32 s1, s0, 0x72
	global_load_dword v178, v[68:69], off nt
	v_lshl_add_u64 v[68:69], v[2:3], 0, s[4:5]
	s_lshl_b32 s4, s1, 8
	s_min_u32 s1, s0, 0x73
	global_load_dword v180, v[68:69], off nt
	v_lshl_add_u64 v[68:69], v[2:3], 0, s[4:5]
	s_lshl_b32 s4, s1, 8
	s_min_u32 s1, s0, 0x74
	global_load_dword v181, v[68:69], off nt
	v_lshl_add_u64 v[68:69], v[2:3], 0, s[4:5]
	s_lshl_b32 s4, s1, 8
	s_min_u32 s1, s0, 0x75
	global_load_dword v182, v[68:69], off nt
	v_lshl_add_u64 v[68:69], v[2:3], 0, s[4:5]
	s_lshl_b32 s4, s1, 8
	s_min_u32 s1, s0, 0x76
	global_load_dword v183, v[68:69], off nt
	v_lshl_add_u64 v[68:69], v[2:3], 0, s[4:5]
	s_lshl_b32 s4, s1, 8
	s_min_u32 s1, s0, 0x77
	global_load_dword v184, v[68:69], off nt
	v_lshl_add_u64 v[68:69], v[2:3], 0, s[4:5]
	s_lshl_b32 s4, s1, 8
	s_min_u32 s1, s0, 0x78
	global_load_dword v185, v[68:69], off nt
	v_lshl_add_u64 v[68:69], v[2:3], 0, s[4:5]
	s_lshl_b32 s4, s1, 8
	s_min_u32 s1, s0, 0x79
	global_load_dword v187, v[68:69], off nt
	v_lshl_add_u64 v[68:69], v[2:3], 0, s[4:5]
	s_lshl_b32 s4, s1, 8
	s_min_u32 s1, s0, 0x7a
	global_load_dword v186, v[68:69], off nt
	v_lshl_add_u64 v[68:69], v[2:3], 0, s[4:5]
	s_lshl_b32 s4, s1, 8
	s_min_u32 s1, s0, 0x7b
	global_load_dword v188, v[68:69], off nt
	v_lshl_add_u64 v[68:69], v[2:3], 0, s[4:5]
	s_lshl_b32 s4, s1, 8
	s_min_u32 s1, s0, 0x7c
	global_load_dword v189, v[68:69], off nt
	v_lshl_add_u64 v[68:69], v[2:3], 0, s[4:5]
	s_lshl_b32 s4, s1, 8
	s_min_u32 s1, s0, 0x7d
	global_load_dword v190, v[68:69], off nt
	v_lshl_add_u64 v[68:69], v[2:3], 0, s[4:5]
	s_lshl_b32 s4, s1, 8
	s_min_u32 s1, s0, 0x7e
	global_load_dword v191, v[68:69], off nt
	v_lshl_add_u64 v[68:69], v[2:3], 0, s[4:5]
	s_lshl_b32 s4, s1, 8
	global_load_dword v192, v[68:69], off nt
	v_lshl_add_u64 v[68:69], v[2:3], 0, s[4:5]
	s_lshl_b32 s4, s0, 6
	v_lshl_add_u64 v[2:3], s[4:5], 2, v[2:3]
	global_load_dword v193, v[68:69], off nt
	global_load_dword v194, v[2:3], off nt
	s_waitcnt vmcnt(0)
; __device__ __forceinline__ void topk_row(const Params& p, int r, int lane, __attribute__((address_space(3))) int* out) {
;     ...
;     for (int i = 0; i < 128; ++i) {
;       const int lim = n - i * 64;
;       const unsigned u = key[i];
;       key[i] = (lo < lim) ? ((u >> 31) ? ~u : (u | 0x80000000u)) : 0u;
;     }
	v_ashrrev_i32_e32 v240, 31, v9
	v_or_b32_e32 v240, 0x80000000, v240
	v_xor_b32_e32 v240, v9, v240
	v_cmp_ge_i32_e64 s[68:69], s15, v0
	s_sub_i32 s0, s15, 63
	v_ashrrev_i32_e32 v241, 31, v8
	v_or_b32_e32 v241, 0x80000000, v241
	v_xor_b32_e32 v241, v8, v241
	v_cmp_gt_i32_e64 s[70:71], s0, v0
	s_add_i32 s0, s15, 0xffffff81
	v_cndmask_b32_e64 v139, 0, v240, s[68:69]
	v_ashrrev_i32_e32 v240, 31, v7
	v_or_b32_e32 v240, 0x80000000, v240
	v_xor_b32_e32 v240, v7, v240
	v_cmp_gt_i32_e64 s[72:73], s0, v0
	s_add_i32 s0, s15, 0xffffff41
	v_cndmask_b32_e64 v138, 0, v241, s[70:71]
	v_ashrrev_i32_e32 v241, 31, v4
	v_or_b32_e32 v241, 0x80000000, v241
	v_xor_b32_e32 v241, v4, v241
	v_cmp_gt_i32_e64 s[74:75], s0, v0
	s_add_i32 s0, s15, 0xffffff01
	v_cndmask_b32_e64 v137, 0, v240, s[72:73]
	v_ashrrev_i32_e32 v240, 31, v1
	v_or_b32_e32 v240, 0x80000000, v240
	v_xor_b32_e32 v240, v1, v240
	v_cmp_gt_i32_e64 s[68:69], s0, v0
	s_add_i32 s0, s15, 0xfffffec1
	v_cndmask_b32_e64 v136, 0, v241, s[74:75]
	v_ashrrev_i32_e32 v241, 31, v5
	v_or_b32_e32 v241, 0x80000000, v241
	v_xor_b32_e32 v241, v5, v241
	v_cmp_gt_i32_e64 s[70:71], s0, v0
	s_add_i32 s0, s15, 0xfffffe81
	v_cndmask_b32_e64 v135, 0, v240, s[68:69]
	v_ashrrev_i32_e32 v240, 31, v6
	v_or_b32_e32 v240, 0x80000000, v240
	v_xor_b32_e32 v240, v6, v240
	v_cmp_gt_i32_e64 s[72:73], s0, v0
	s_add_i32 s0, s15, 0xfffffe41
	v_cndmask_b32_e64 v134, 0, v241, s[70:71]
	v_ashrrev_i32_e32 v241, 31, v11
	v_or_b32_e32 v241, 0x80000000, v241
	v_xor_b32_e32 v241, v11, v241
	v_cmp_gt_i32_e64 s[74:75], s0, v0
	s_add_i32 s0, s15, 0xfffffe01
	v_cndmask_b32_e64 v133, 0, v240, s[72:73]
	v_ashrrev_i32_e32 v240, 31, v10
	v_or_b32_e32 v240, 0x80000000, v240
	v_xor_b32_e32 v240, v10, v240
	v_cmp_gt_i32_e64 s[68:69], s0, v0
	s_add_i32 s0, s15, 0xfffffdc1
	v_cndmask_b32_e64 v132, 0, v241, s[74:75]
	v_ashrrev_i32_e32 v241, 31, v12
	v_or_b32_e32 v241, 0x80000000, v241
	v_xor_b32_e32 v241, v12, v241
	v_cmp_gt_i32_e64 s[70:71], s0, v0
	s_add_i32 s0, s15, 0xfffffd81
	v_cndmask_b32_e64 v131, 0, v240, s[68:69]
	v_ashrrev_i32_e32 v240, 31, v13
	v_or_b32_e32 v240, 0x80000000, v240
	v_xor_b32_e32 v240, v13, v240
	v_cmp_gt_i32_e64 s[72:73], s0, v0
	s_add_i32 s0, s15, 0xfffffd41
	v_cndmask_b32_e64 v130, 0, v241, s[70:71]
	v_ashrrev_i32_e32 v241, 31, v14
	v_or_b32_e32 v241, 0x80000000, v241
	v_xor_b32_e32 v241, v14, v241
	v_cmp_gt_i32_e64 s[74:75], s0, v0
	s_add_i32 s0, s15, 0xfffffd01
	v_cndmask_b32_e64 v129, 0, v240, s[72:73]
	v_ashrrev_i32_e32 v240, 31, v15
	v_or_b32_e32 v240, 0x80000000, v240
	v_xor_b32_e32 v240, v15, v240
	v_cmp_gt_i32_e64 s[68:69], s0, v0
	s_add_i32 s0, s15, 0xfffffcc1
	v_cndmask_b32_e64 v128, 0, v241, s[74:75]
	v_ashrrev_i32_e32 v241, 31, v16
	v_or_b32_e32 v241, 0x80000000, v241
	v_xor_b32_e32 v241, v16, v241
	v_cmp_gt_i32_e64 s[70:71], s0, v0
	s_add_i32 s0, s15, 0xfffffc81
	v_cndmask_b32_e64 v127, 0, v240, s[68:69]
	v_ashrrev_i32_e32 v240, 31, v17
	v_or_b32_e32 v240, 0x80000000, v240
	v_xor_b32_e32 v240, v17, v240
	v_cmp_gt_i32_e64 s[72:73], s0, v0
	s_add_i32 s0, s15, 0xfffffc41
	v_cndmask_b32_e64 v126, 0, v241, s[70:71]
	v_ashrrev_i32_e32 v241, 31, v19
	v_or_b32_e32 v241, 0x80000000, v241
	v_xor_b32_e32 v241, v19, v241
	v_cmp_gt_i32_e64 s[74:75], s0, v0
	s_add_i32 s0, s15, 0xfffffc01
	v_cndmask_b32_e64 v125, 0, v240, s[72:73]
	v_ashrrev_i32_e32 v240, 31, v18
	v_or_b32_e32 v240, 0x80000000, v240
	v_xor_b32_e32 v240, v18, v240
	v_cmp_gt_i32_e64 s[68:69], s0, v0
	s_add_i32 s0, s15, 0xfffffbc1
	v_cndmask_b32_e64 v124, 0, v241, s[74:75]
	v_ashrrev_i32_e32 v241, 31, v20
	v_or_b32_e32 v241, 0x80000000, v241
	v_xor_b32_e32 v241, v20, v241
	v_cmp_gt_i32_e64 s[70:71], s0, v0
	s_add_i32 s0, s15, 0xfffffb81
	v_cndmask_b32_e64 v114, 0, v240, s[68:69]
	v_ashrrev_i32_e32 v240, 31, v21
	v_or_b32_e32 v240, 0x80000000, v240
	v_xor_b32_e32 v240, v21, v240
	v_cmp_gt_i32_e64 s[72:73], s0, v0
	s_add_i32 s0, s15, 0xfffffb41
	v_cndmask_b32_e64 v113, 0, v241, s[70:71]
	v_ashrrev_i32_e32 v241, 31, v22
	v_or_b32_e32 v241, 0x80000000, v241
	v_xor_b32_e32 v241, v22, v241
	v_cmp_gt_i32_e64 s[74:75], s0, v0
	s_add_i32 s0, s15, 0xfffffb01
	v_cndmask_b32_e64 v112, 0, v240, s[72:73]
	v_ashrrev_i32_e32 v240, 31, v23
	v_or_b32_e32 v240, 0x80000000, v240
	v_xor_b32_e32 v240, v23, v240
	v_cmp_gt_i32_e64 s[68:69], s0, v0
	s_add_i32 s0, s15, 0xfffffac1
	v_cndmask_b32_e64 v111, 0, v241, s[74:75]
	v_ashrrev_i32_e32 v241, 31, v24
	v_or_b32_e32 v241, 0x80000000, v241
	v_xor_b32_e32 v241, v24, v241
	v_cmp_gt_i32_e64 s[70:71], s0, v0
	s_add_i32 s0, s15, 0xfffffa81
	v_cndmask_b32_e64 v110, 0, v240, s[68:69]
	v_ashrrev_i32_e32 v240, 31, v25
	v_or_b32_e32 v240, 0x80000000, v240
	v_xor_b32_e32 v240, v25, v240
	v_cmp_gt_i32_e64 s[72:73], s0, v0
	s_add_i32 s0, s15, 0xfffffa41
	v_cndmask_b32_e64 v109, 0, v241, s[70:71]
	v_ashrrev_i32_e32 v241, 31, v27
	v_or_b32_e32 v241, 0x80000000, v241
	v_xor_b32_e32 v241, v27, v241
	v_cmp_gt_i32_e64 s[74:75], s0, v0
	s_add_i32 s0, s15, 0xfffffa01
	v_cndmask_b32_e64 v108, 0, v240, s[72:73]
	v_ashrrev_i32_e32 v240, 31, v26
	v_or_b32_e32 v240, 0x80000000, v240
	v_xor_b32_e32 v240, v26, v240
	v_cmp_gt_i32_e64 s[68:69], s0, v0
	s_add_i32 s0, s15, 0xfffff9c1
	v_cndmask_b32_e64 v107, 0, v241, s[74:75]
	v_ashrrev_i32_e32 v241, 31, v28
	v_or_b32_e32 v241, 0x80000000, v241
	v_xor_b32_e32 v241, v28, v241
	v_cmp_gt_i32_e64 s[70:71], s0, v0
	s_add_i32 s0, s15, 0xfffff981
	v_cndmask_b32_e64 v106, 0, v240, s[68:69]
	v_ashrrev_i32_e32 v240, 31, v29
	v_or_b32_e32 v240, 0x80000000, v240
	v_xor_b32_e32 v240, v29, v240
	v_cmp_gt_i32_e64 s[72:73], s0, v0
	s_add_i32 s0, s15, 0xfffff941
	v_cndmask_b32_e64 v105, 0, v241, s[70:71]
	v_ashrrev_i32_e32 v241, 31, v30
; __device__ __forceinline__ void topk_row(const Params& p, int r, int lane, __attribute__((address_space(3))) int* out) {
;     ...
;     for (int i = 0; i < 128; ++i) {
;       const int lim = n - i * 64;
;       const unsigned u = key[i];
;       key[i] = (lo < lim) ? ((u >> 31) ? ~u : (u | 0x80000000u)) : 0u;
;     }
	v_or_b32_e32 v241, 0x80000000, v241
	v_xor_b32_e32 v241, v30, v241
	v_cmp_gt_i32_e64 s[74:75], s0, v0
	s_add_i32 s0, s15, 0xfffff901
	v_cndmask_b32_e64 v104, 0, v240, s[72:73]
	v_ashrrev_i32_e32 v240, 31, v31
	v_or_b32_e32 v240, 0x80000000, v240
	v_xor_b32_e32 v240, v31, v240
	v_cmp_gt_i32_e64 s[68:69], s0, v0
	s_add_i32 s0, s15, 0xfffff8c1
	v_cndmask_b32_e64 v103, 0, v241, s[74:75]
	v_ashrrev_i32_e32 v241, 31, v32
	v_or_b32_e32 v241, 0x80000000, v241
	v_xor_b32_e32 v241, v32, v241
	v_cmp_gt_i32_e64 s[70:71], s0, v0
	s_add_i32 s0, s15, 0xfffff881
	v_cndmask_b32_e64 v102, 0, v240, s[68:69]
	v_ashrrev_i32_e32 v240, 31, v34
	v_or_b32_e32 v240, 0x80000000, v240
	v_xor_b32_e32 v240, v34, v240
	v_cmp_gt_i32_e64 s[72:73], s0, v0
	s_add_i32 s0, s15, 0xfffff841
	v_cndmask_b32_e64 v101, 0, v241, s[70:71]
	v_ashrrev_i32_e32 v241, 31, v36
	v_or_b32_e32 v241, 0x80000000, v241
	v_xor_b32_e32 v241, v36, v241
	v_cmp_gt_i32_e64 s[74:75], s0, v0
	s_add_i32 s0, s15, 0xfffff801
	v_cndmask_b32_e64 v100, 0, v240, s[72:73]
	v_ashrrev_i32_e32 v240, 31, v35
	v_or_b32_e32 v240, 0x80000000, v240
	v_xor_b32_e32 v240, v35, v240
	v_cmp_gt_i32_e64 s[68:69], s0, v0
	s_add_i32 s0, s15, 0xfffff7c1
	v_cndmask_b32_e64 v99, 0, v241, s[74:75]
	v_ashrrev_i32_e32 v241, 31, v37
	v_or_b32_e32 v241, 0x80000000, v241
	v_xor_b32_e32 v241, v37, v241
	v_cmp_gt_i32_e64 s[70:71], s0, v0
	s_add_i32 s0, s15, 0xfffff781
	v_cndmask_b32_e64 v98, 0, v240, s[68:69]
	v_ashrrev_i32_e32 v240, 31, v38
	v_or_b32_e32 v240, 0x80000000, v240
	v_xor_b32_e32 v240, v38, v240
	v_cmp_gt_i32_e64 s[72:73], s0, v0
	s_add_i32 s0, s15, 0xfffff741
	v_cndmask_b32_e64 v97, 0, v241, s[70:71]
	v_ashrrev_i32_e32 v241, 31, v39
	v_or_b32_e32 v241, 0x80000000, v241
	v_xor_b32_e32 v241, v39, v241
	v_cmp_gt_i32_e64 s[74:75], s0, v0
	s_add_i32 s0, s15, 0xfffff701
	v_cndmask_b32_e64 v96, 0, v240, s[72:73]
	v_ashrrev_i32_e32 v240, 31, v40
	v_or_b32_e32 v240, 0x80000000, v240
	v_xor_b32_e32 v240, v40, v240
	v_cmp_gt_i32_e64 s[68:69], s0, v0
	s_add_i32 s0, s15, 0xfffff6c1
	v_cndmask_b32_e64 v95, 0, v241, s[74:75]
	v_ashrrev_i32_e32 v241, 31, v41
	v_or_b32_e32 v241, 0x80000000, v241
	v_xor_b32_e32 v241, v41, v241
	v_cmp_gt_i32_e64 s[70:71], s0, v0
	s_add_i32 s0, s15, 0xfffff681
	v_cndmask_b32_e64 v94, 0, v240, s[68:69]
	v_ashrrev_i32_e32 v240, 31, v42
	v_or_b32_e32 v240, 0x80000000, v240
	v_xor_b32_e32 v240, v42, v240
	v_cmp_gt_i32_e64 s[72:73], s0, v0
	s_add_i32 s0, s15, 0xfffff641
	v_cndmask_b32_e64 v93, 0, v241, s[70:71]
	v_ashrrev_i32_e32 v241, 31, v44
	v_or_b32_e32 v241, 0x80000000, v241
	v_xor_b32_e32 v241, v44, v241
	v_cmp_gt_i32_e64 s[74:75], s0, v0
	s_add_i32 s0, s15, 0xfffff601
	v_cndmask_b32_e64 v92, 0, v240, s[72:73]
	v_ashrrev_i32_e32 v240, 31, v43
	v_or_b32_e32 v240, 0x80000000, v240
	v_xor_b32_e32 v240, v43, v240
	v_cmp_gt_i32_e64 s[68:69], s0, v0
	s_add_i32 s0, s15, 0xfffff5c1
	v_cndmask_b32_e64 v91, 0, v241, s[74:75]
	v_ashrrev_i32_e32 v241, 31, v45
	v_or_b32_e32 v241, 0x80000000, v241
	v_xor_b32_e32 v241, v45, v241
	v_cmp_gt_i32_e64 s[70:71], s0, v0
	s_add_i32 s0, s15, 0xfffff581
	v_cndmask_b32_e64 v90, 0, v240, s[68:69]
	v_ashrrev_i32_e32 v240, 31, v46
	v_or_b32_e32 v240, 0x80000000, v240
	v_xor_b32_e32 v240, v46, v240
	v_cmp_gt_i32_e64 s[72:73], s0, v0
	s_add_i32 s0, s15, 0xfffff541
	v_cndmask_b32_e64 v89, 0, v241, s[70:71]
	v_ashrrev_i32_e32 v241, 31, v47
	v_or_b32_e32 v241, 0x80000000, v241
	v_xor_b32_e32 v241, v47, v241
	v_cmp_gt_i32_e64 s[74:75], s0, v0
	s_add_i32 s0, s15, 0xfffff501
	v_cndmask_b32_e64 v88, 0, v240, s[72:73]
	v_ashrrev_i32_e32 v240, 31, v48
	v_or_b32_e32 v240, 0x80000000, v240
	v_xor_b32_e32 v240, v48, v240
	v_cmp_gt_i32_e64 s[68:69], s0, v0
	s_add_i32 s0, s15, 0xfffff4c1
	v_cndmask_b32_e64 v87, 0, v241, s[74:75]
	v_ashrrev_i32_e32 v241, 31, v49
	v_or_b32_e32 v241, 0x80000000, v241
	v_xor_b32_e32 v241, v49, v241
	v_cmp_gt_i32_e64 s[70:71], s0, v0
	s_add_i32 s0, s15, 0xfffff481
	v_cndmask_b32_e64 v86, 0, v240, s[68:69]
	v_ashrrev_i32_e32 v240, 31, v50
	v_or_b32_e32 v240, 0x80000000, v240
	v_xor_b32_e32 v240, v50, v240
	v_cmp_gt_i32_e64 s[72:73], s0, v0
	s_add_i32 s0, s15, 0xfffff441
	v_cndmask_b32_e64 v85, 0, v241, s[70:71]
	v_ashrrev_i32_e32 v241, 31, v52
	v_or_b32_e32 v241, 0x80000000, v241
	v_xor_b32_e32 v241, v52, v241
	v_cmp_gt_i32_e64 s[74:75], s0, v0
	s_add_i32 s0, s15, 0xfffff401
	v_cndmask_b32_e64 v84, 0, v240, s[72:73]
	v_ashrrev_i32_e32 v240, 31, v51
	v_or_b32_e32 v240, 0x80000000, v240
	v_xor_b32_e32 v240, v51, v240
	v_cmp_gt_i32_e64 s[68:69], s0, v0
	s_add_i32 s0, s15, 0xfffff3c1
	v_cndmask_b32_e64 v83, 0, v241, s[74:75]
	v_ashrrev_i32_e32 v241, 31, v53
	v_or_b32_e32 v241, 0x80000000, v241
	v_xor_b32_e32 v241, v53, v241
	v_cmp_gt_i32_e64 s[70:71], s0, v0
	s_add_i32 s0, s15, 0xfffff381
	v_cndmask_b32_e64 v82, 0, v240, s[68:69]
	v_ashrrev_i32_e32 v240, 31, v54
	v_or_b32_e32 v240, 0x80000000, v240
	v_xor_b32_e32 v240, v54, v240
	v_cmp_gt_i32_e64 s[72:73], s0, v0
	s_add_i32 s0, s15, 0xfffff341
	v_cndmask_b32_e64 v81, 0, v241, s[70:71]
	v_ashrrev_i32_e32 v241, 31, v55
	v_or_b32_e32 v241, 0x80000000, v241
	v_xor_b32_e32 v241, v55, v241
	v_cmp_gt_i32_e64 s[74:75], s0, v0
	s_add_i32 s0, s15, 0xfffff301
	v_cndmask_b32_e64 v80, 0, v240, s[72:73]
	v_ashrrev_i32_e32 v240, 31, v56
	v_or_b32_e32 v240, 0x80000000, v240
	v_xor_b32_e32 v240, v56, v240
	v_cmp_gt_i32_e64 s[68:69], s0, v0
	s_add_i32 s0, s15, 0xfffff2c1
	v_cndmask_b32_e64 v79, 0, v241, s[74:75]
	v_ashrrev_i32_e32 v241, 31, v57
	v_or_b32_e32 v241, 0x80000000, v241
	v_xor_b32_e32 v241, v57, v241
	v_cmp_gt_i32_e64 s[70:71], s0, v0
	s_add_i32 s0, s15, 0xfffff281
	v_cndmask_b32_e64 v78, 0, v240, s[68:69]
	v_ashrrev_i32_e32 v240, 31, v58
; __device__ __forceinline__ void topk_row(const Params& p, int r, int lane, __attribute__((address_space(3))) int* out) {
;     ...
;     for (int i = 0; i < 128; ++i) {
;       const int lim = n - i * 64;
;       const unsigned u = key[i];
;       key[i] = (lo < lim) ? ((u >> 31) ? ~u : (u | 0x80000000u)) : 0u;
;     }
	v_or_b32_e32 v240, 0x80000000, v240
	v_xor_b32_e32 v240, v58, v240
	v_cmp_gt_i32_e64 s[72:73], s0, v0
	s_add_i32 s0, s15, 0xfffff241
	v_cndmask_b32_e64 v77, 0, v241, s[70:71]
	v_ashrrev_i32_e32 v241, 31, v60
	v_or_b32_e32 v241, 0x80000000, v241
	v_xor_b32_e32 v241, v60, v241
	v_cmp_gt_i32_e64 s[74:75], s0, v0
	s_add_i32 s0, s15, 0xfffff201
	v_cndmask_b32_e64 v76, 0, v240, s[72:73]
	v_ashrrev_i32_e32 v240, 31, v59
	v_or_b32_e32 v240, 0x80000000, v240
	v_xor_b32_e32 v240, v59, v240
	v_cmp_gt_i32_e64 s[68:69], s0, v0
	s_add_i32 s0, s15, 0xfffff1c1
	v_cndmask_b32_e64 v75, 0, v241, s[74:75]
	v_ashrrev_i32_e32 v241, 31, v61
	v_or_b32_e32 v241, 0x80000000, v241
	v_xor_b32_e32 v241, v61, v241
	v_cmp_gt_i32_e64 s[70:71], s0, v0
	s_add_i32 s0, s15, 0xfffff181
	v_cndmask_b32_e64 v74, 0, v240, s[68:69]
	v_ashrrev_i32_e32 v240, 31, v62
	v_or_b32_e32 v240, 0x80000000, v240
	v_xor_b32_e32 v240, v62, v240
	v_cmp_gt_i32_e64 s[72:73], s0, v0
	s_add_i32 s0, s15, 0xfffff141
	v_cndmask_b32_e64 v73, 0, v241, s[70:71]
	v_ashrrev_i32_e32 v241, 31, v63
	v_or_b32_e32 v241, 0x80000000, v241
	v_xor_b32_e32 v241, v63, v241
	v_cmp_gt_i32_e64 s[74:75], s0, v0
	s_add_i32 s0, s15, 0xfffff101
	v_cndmask_b32_e64 v72, 0, v240, s[72:73]
	v_ashrrev_i32_e32 v240, 31, v64
	v_or_b32_e32 v240, 0x80000000, v240
	v_xor_b32_e32 v240, v64, v240
	v_cmp_gt_i32_e64 s[68:69], s0, v0
	s_add_i32 s0, s15, 0xfffff0c1
	v_cndmask_b32_e64 v71, 0, v241, s[74:75]
	v_ashrrev_i32_e32 v241, 31, v65
	v_or_b32_e32 v241, 0x80000000, v241
	v_xor_b32_e32 v241, v65, v241
	v_cmp_gt_i32_e64 s[70:71], s0, v0
	s_add_i32 s0, s15, 0xfffff081
	v_cndmask_b32_e64 v70, 0, v240, s[68:69]
	v_ashrrev_i32_e32 v240, 31, v66
	v_or_b32_e32 v240, 0x80000000, v240
	v_xor_b32_e32 v240, v66, v240
	v_cmp_gt_i32_e64 s[72:73], s0, v0
	s_add_i32 s0, s15, 0xfffff041
	v_cndmask_b32_e64 v69, 0, v241, s[70:71]
	v_ashrrev_i32_e32 v241, 31, v67
	v_or_b32_e32 v241, 0x80000000, v241
	v_xor_b32_e32 v241, v67, v241
	v_cmp_gt_i32_e64 s[74:75], s0, v0
	s_add_i32 s0, s15, 0xfffff001
	v_cndmask_b32_e64 v68, 0, v240, s[72:73]
	v_ashrrev_i32_e32 v240, 31, v115
	v_or_b32_e32 v240, 0x80000000, v240
	v_xor_b32_e32 v240, v115, v240
	v_cmp_gt_i32_e64 s[68:69], s0, v0
	s_add_i32 s0, s15, 0xffffefc1
	v_cndmask_b32_e64 v67, 0, v241, s[74:75]
	v_ashrrev_i32_e32 v241, 31, v116
	v_or_b32_e32 v241, 0x80000000, v241
	v_xor_b32_e32 v241, v116, v241
	v_cmp_gt_i32_e64 s[70:71], s0, v0
	s_add_i32 s0, s15, 0xffffef81
	v_cndmask_b32_e64 v66, 0, v240, s[68:69]
	s_waitcnt vmcnt(61)
	v_ashrrev_i32_e32 v240, 31, v117
	v_or_b32_e32 v240, 0x80000000, v240
	v_xor_b32_e32 v240, v117, v240
	v_cmp_gt_i32_e64 s[72:73], s0, v0
	s_add_i32 s0, s15, 0xffffef41
	v_cndmask_b32_e64 v65, 0, v241, s[70:71]
	s_waitcnt vmcnt(60)
	v_ashrrev_i32_e32 v241, 31, v118
	v_or_b32_e32 v241, 0x80000000, v241
	v_xor_b32_e32 v241, v118, v241
	v_cmp_gt_i32_e64 s[74:75], s0, v0
	s_add_i32 s0, s15, 0xffffef01
	v_cndmask_b32_e64 v64, 0, v240, s[72:73]
	s_waitcnt vmcnt(59)
	v_ashrrev_i32_e32 v240, 31, v119
	v_or_b32_e32 v240, 0x80000000, v240
	v_xor_b32_e32 v240, v119, v240
	v_cmp_gt_i32_e64 s[68:69], s0, v0
	s_add_i32 s0, s15, 0xffffeec1
	v_cndmask_b32_e64 v63, 0, v241, s[74:75]
	s_waitcnt vmcnt(58)
	v_ashrrev_i32_e32 v241, 31, v120
	v_or_b32_e32 v241, 0x80000000, v241
	v_xor_b32_e32 v241, v120, v241
	v_cmp_gt_i32_e64 s[70:71], s0, v0
	s_add_i32 s0, s15, 0xffffee81
	v_cndmask_b32_e64 v62, 0, v240, s[68:69]
	s_waitcnt vmcnt(57)
	v_ashrrev_i32_e32 v240, 31, v121
	v_or_b32_e32 v240, 0x80000000, v240
	v_xor_b32_e32 v240, v121, v240
	v_cmp_gt_i32_e64 s[72:73], s0, v0
	s_add_i32 s0, s15, 0xffffee41
	v_cndmask_b32_e64 v61, 0, v241, s[70:71]
	s_waitcnt vmcnt(56)
	v_ashrrev_i32_e32 v241, 31, v123
	v_or_b32_e32 v241, 0x80000000, v241
	v_xor_b32_e32 v241, v123, v241
	v_cmp_gt_i32_e64 s[74:75], s0, v0
	s_add_i32 s0, s15, 0xffffee01
	v_cndmask_b32_e64 v60, 0, v240, s[72:73]
	s_waitcnt vmcnt(55)
	v_ashrrev_i32_e32 v240, 31, v122
	v_or_b32_e32 v240, 0x80000000, v240
	v_xor_b32_e32 v240, v122, v240
	v_cmp_gt_i32_e64 s[68:69], s0, v0
	s_add_i32 s0, s15, 0xffffedc1
	v_cndmask_b32_e64 v59, 0, v241, s[74:75]
	s_waitcnt vmcnt(54)
	v_ashrrev_i32_e32 v241, 31, v140
	v_or_b32_e32 v241, 0x80000000, v241
	v_xor_b32_e32 v241, v140, v241
	v_cmp_gt_i32_e64 s[70:71], s0, v0
	s_add_i32 s0, s15, 0xffffed81
	v_cndmask_b32_e64 v58, 0, v240, s[68:69]
	s_waitcnt vmcnt(53)
	v_ashrrev_i32_e32 v240, 31, v141
	v_or_b32_e32 v240, 0x80000000, v240
	v_xor_b32_e32 v240, v141, v240
	v_cmp_gt_i32_e64 s[72:73], s0, v0
	s_add_i32 s0, s15, 0xffffed41
	v_cndmask_b32_e64 v57, 0, v241, s[70:71]
	s_waitcnt vmcnt(52)
	v_ashrrev_i32_e32 v241, 31, v142
	v_or_b32_e32 v241, 0x80000000, v241
	v_xor_b32_e32 v241, v142, v241
	v_cmp_gt_i32_e64 s[74:75], s0, v0
	s_add_i32 s0, s15, 0xffffed01
	v_cndmask_b32_e64 v56, 0, v240, s[72:73]
	s_waitcnt vmcnt(51)
	v_ashrrev_i32_e32 v240, 31, v143
	v_or_b32_e32 v240, 0x80000000, v240
	v_xor_b32_e32 v240, v143, v240
	v_cmp_gt_i32_e64 s[68:69], s0, v0
	s_add_i32 s0, s15, 0xffffecc1
	v_cndmask_b32_e64 v55, 0, v241, s[74:75]
	s_waitcnt vmcnt(50)
	v_ashrrev_i32_e32 v241, 31, v144
	v_or_b32_e32 v241, 0x80000000, v241
	v_xor_b32_e32 v241, v144, v241
	v_cmp_gt_i32_e64 s[70:71], s0, v0
	s_add_i32 s0, s15, 0xffffec81
	v_cndmask_b32_e64 v54, 0, v240, s[68:69]
	s_waitcnt vmcnt(49)
	v_ashrrev_i32_e32 v240, 31, v145
	v_or_b32_e32 v240, 0x80000000, v240
	v_xor_b32_e32 v240, v145, v240
	v_cmp_gt_i32_e64 s[72:73], s0, v0
	s_add_i32 s0, s15, 0xffffec41
	v_cndmask_b32_e64 v53, 0, v241, s[70:71]
	s_waitcnt vmcnt(48)
	v_ashrrev_i32_e32 v241, 31, v147
	v_or_b32_e32 v241, 0x80000000, v241
	v_xor_b32_e32 v241, v147, v241
	v_cmp_gt_i32_e64 s[74:75], s0, v0
	s_add_i32 s0, s15, 0xffffec01
	v_cndmask_b32_e64 v52, 0, v240, s[72:73]
	s_waitcnt vmcnt(47)
; __device__ __forceinline__ void topk_row(const Params& p, int r, int lane, __attribute__((address_space(3))) int* out) {
;     ...
;     for (int i = 0; i < 128; ++i) {
;       const int lim = n - i * 64;
;       const unsigned u = key[i];
;       key[i] = (lo < lim) ? ((u >> 31) ? ~u : (u | 0x80000000u)) : 0u;
;     }
	v_ashrrev_i32_e32 v240, 31, v146
	v_or_b32_e32 v240, 0x80000000, v240
	v_xor_b32_e32 v240, v146, v240
	v_cmp_gt_i32_e64 s[68:69], s0, v0
	s_add_i32 s0, s15, 0xffffebc1
	v_cndmask_b32_e64 v51, 0, v241, s[74:75]
	s_waitcnt vmcnt(46)
	v_ashrrev_i32_e32 v241, 31, v148
	v_or_b32_e32 v241, 0x80000000, v241
	v_xor_b32_e32 v241, v148, v241
	v_cmp_gt_i32_e64 s[70:71], s0, v0
	s_add_i32 s0, s15, 0xffffeb81
	v_cndmask_b32_e64 v50, 0, v240, s[68:69]
	s_waitcnt vmcnt(45)
	v_ashrrev_i32_e32 v240, 31, v149
	v_or_b32_e32 v240, 0x80000000, v240
	v_xor_b32_e32 v240, v149, v240
	v_cmp_gt_i32_e64 s[72:73], s0, v0
	s_add_i32 s0, s15, 0xffffeb41
	v_cndmask_b32_e64 v49, 0, v241, s[70:71]
	s_waitcnt vmcnt(44)
	v_ashrrev_i32_e32 v241, 31, v150
	v_or_b32_e32 v241, 0x80000000, v241
	v_xor_b32_e32 v241, v150, v241
	v_cmp_gt_i32_e64 s[74:75], s0, v0
	s_add_i32 s0, s15, 0xffffeb01
	v_cndmask_b32_e64 v48, 0, v240, s[72:73]
	s_waitcnt vmcnt(43)
	v_ashrrev_i32_e32 v240, 31, v151
	v_or_b32_e32 v240, 0x80000000, v240
	v_xor_b32_e32 v240, v151, v240
	v_cmp_gt_i32_e64 s[68:69], s0, v0
	s_add_i32 s0, s15, 0xffffeac1
	v_cndmask_b32_e64 v47, 0, v241, s[74:75]
	s_waitcnt vmcnt(42)
	v_ashrrev_i32_e32 v241, 31, v152
	v_or_b32_e32 v241, 0x80000000, v241
	v_xor_b32_e32 v241, v152, v241
	v_cmp_gt_i32_e64 s[70:71], s0, v0
	s_add_i32 s0, s15, 0xffffea81
	v_cndmask_b32_e64 v46, 0, v240, s[68:69]
	s_waitcnt vmcnt(41)
	v_ashrrev_i32_e32 v240, 31, v153
	v_or_b32_e32 v240, 0x80000000, v240
	v_xor_b32_e32 v240, v153, v240
	v_cmp_gt_i32_e64 s[72:73], s0, v0
	s_add_i32 s0, s15, 0xffffea41
	v_cndmask_b32_e64 v45, 0, v241, s[70:71]
	s_waitcnt vmcnt(40)
	v_ashrrev_i32_e32 v241, 31, v155
	v_or_b32_e32 v241, 0x80000000, v241
	v_xor_b32_e32 v241, v155, v241
	v_cmp_gt_i32_e64 s[74:75], s0, v0
	s_add_i32 s0, s15, 0xffffea01
	v_cndmask_b32_e64 v44, 0, v240, s[72:73]
	s_waitcnt vmcnt(39)
	v_ashrrev_i32_e32 v240, 31, v154
	v_or_b32_e32 v240, 0x80000000, v240
	v_xor_b32_e32 v240, v154, v240
	v_cmp_gt_i32_e64 s[68:69], s0, v0
	s_add_i32 s0, s15, 0xffffe9c1
	v_cndmask_b32_e64 v43, 0, v241, s[74:75]
	s_waitcnt vmcnt(38)
	v_ashrrev_i32_e32 v241, 31, v156
	v_or_b32_e32 v241, 0x80000000, v241
	v_xor_b32_e32 v241, v156, v241
	v_cmp_gt_i32_e64 s[70:71], s0, v0
	s_add_i32 s0, s15, 0xffffe981
	v_cndmask_b32_e64 v42, 0, v240, s[68:69]
	s_waitcnt vmcnt(37)
	v_ashrrev_i32_e32 v240, 31, v157
	v_or_b32_e32 v240, 0x80000000, v240
	v_xor_b32_e32 v240, v157, v240
	v_cmp_gt_i32_e64 s[72:73], s0, v0
	s_add_i32 s0, s15, 0xffffe941
	v_cndmask_b32_e64 v41, 0, v241, s[70:71]
	s_waitcnt vmcnt(36)
	v_ashrrev_i32_e32 v241, 31, v158
	v_or_b32_e32 v241, 0x80000000, v241
	v_xor_b32_e32 v241, v158, v241
	v_cmp_gt_i32_e64 s[74:75], s0, v0
	s_add_i32 s0, s15, 0xffffe901
	v_cndmask_b32_e64 v40, 0, v240, s[72:73]
	s_waitcnt vmcnt(35)
	v_ashrrev_i32_e32 v240, 31, v159
	v_or_b32_e32 v240, 0x80000000, v240
	v_xor_b32_e32 v240, v159, v240
	v_cmp_gt_i32_e64 s[68:69], s0, v0
	s_add_i32 s0, s15, 0xffffe8c1
	v_cndmask_b32_e64 v39, 0, v241, s[74:75]
	s_waitcnt vmcnt(34)
	v_ashrrev_i32_e32 v241, 31, v160
	v_or_b32_e32 v241, 0x80000000, v241
	v_xor_b32_e32 v241, v160, v241
	v_cmp_gt_i32_e64 s[70:71], s0, v0
	s_add_i32 s0, s15, 0xffffe881
	v_cndmask_b32_e64 v38, 0, v240, s[68:69]
	s_waitcnt vmcnt(33)
	v_ashrrev_i32_e32 v240, 31, v161
	v_or_b32_e32 v240, 0x80000000, v240
	v_xor_b32_e32 v240, v161, v240
	v_cmp_gt_i32_e64 s[72:73], s0, v0
	s_add_i32 s0, s15, 0xffffe841
	v_cndmask_b32_e64 v37, 0, v241, s[70:71]
	s_waitcnt vmcnt(32)
	v_ashrrev_i32_e32 v241, 31, v163
	v_or_b32_e32 v241, 0x80000000, v241
	v_xor_b32_e32 v241, v163, v241
	v_cmp_gt_i32_e64 s[74:75], s0, v0
	s_add_i32 s0, s15, 0xffffe801
	v_cndmask_b32_e64 v36, 0, v240, s[72:73]
	s_waitcnt vmcnt(31)
	v_ashrrev_i32_e32 v240, 31, v162
	v_or_b32_e32 v240, 0x80000000, v240
	v_xor_b32_e32 v240, v162, v240
	v_cmp_gt_i32_e64 s[68:69], s0, v0
	s_add_i32 s0, s15, 0xffffe7c1
	v_cndmask_b32_e64 v35, 0, v241, s[74:75]
	s_waitcnt vmcnt(30)
	v_ashrrev_i32_e32 v241, 31, v164
	v_or_b32_e32 v241, 0x80000000, v241
	v_xor_b32_e32 v241, v164, v241
	v_cmp_gt_i32_e64 s[70:71], s0, v0
	s_add_i32 s0, s15, 0xffffe781
	v_cndmask_b32_e64 v34, 0, v240, s[68:69]
	s_waitcnt vmcnt(29)
	v_ashrrev_i32_e32 v240, 31, v165
	v_or_b32_e32 v240, 0x80000000, v240
	v_xor_b32_e32 v240, v165, v240
	v_cmp_gt_i32_e64 s[72:73], s0, v0
	s_add_i32 s0, s15, 0xffffe741
	v_cndmask_b32_e64 v32, 0, v241, s[70:71]
	s_waitcnt vmcnt(28)
	v_ashrrev_i32_e32 v241, 31, v166
	v_or_b32_e32 v241, 0x80000000, v241
	v_xor_b32_e32 v241, v166, v241
	v_cmp_gt_i32_e64 s[74:75], s0, v0
	s_add_i32 s0, s15, 0xffffe701
	v_cndmask_b32_e64 v31, 0, v240, s[72:73]
	s_waitcnt vmcnt(27)
	v_ashrrev_i32_e32 v240, 31, v167
	v_or_b32_e32 v240, 0x80000000, v240
	v_xor_b32_e32 v240, v167, v240
	v_cmp_gt_i32_e64 s[68:69], s0, v0
	s_add_i32 s0, s15, 0xffffe6c1
	v_cndmask_b32_e64 v30, 0, v241, s[74:75]
	s_waitcnt vmcnt(26)
	v_ashrrev_i32_e32 v241, 31, v168
	v_or_b32_e32 v241, 0x80000000, v241
	v_xor_b32_e32 v241, v168, v241
	v_cmp_gt_i32_e64 s[70:71], s0, v0
	s_add_i32 s0, s15, 0xffffe681
	v_cndmask_b32_e64 v29, 0, v240, s[68:69]
	s_waitcnt vmcnt(25)
	v_ashrrev_i32_e32 v240, 31, v169
	v_or_b32_e32 v240, 0x80000000, v240
	v_xor_b32_e32 v240, v169, v240
	v_cmp_gt_i32_e64 s[72:73], s0, v0
	s_add_i32 s0, s15, 0xffffe641
	v_cndmask_b32_e64 v28, 0, v241, s[70:71]
	s_waitcnt vmcnt(24)
	v_ashrrev_i32_e32 v241, 31, v171
	v_or_b32_e32 v241, 0x80000000, v241
	v_xor_b32_e32 v241, v171, v241
	v_cmp_gt_i32_e64 s[74:75], s0, v0
	s_add_i32 s0, s15, 0xffffe601
	v_cndmask_b32_e64 v27, 0, v240, s[72:73]
	s_waitcnt vmcnt(23)
; __device__ __forceinline__ void topk_row(const Params& p, int r, int lane, __attribute__((address_space(3))) int* out) {
;     ...
;     for (int i = 0; i < 128; ++i) {
;       const int lim = n - i * 64;
;       const unsigned u = key[i];
;       key[i] = (lo < lim) ? ((u >> 31) ? ~u : (u | 0x80000000u)) : 0u;
;     }
;     ...
;     unsigned Tv = 0u;
;     bool exact = false;
;     ...
;       const unsigned cand = Tv | (1u << bit);
;       int c = 0;
; #pragma unroll
;       for (int blk = 0; blk < 8; ++blk) {
;         if (blk * 16 < nch) {
; #pragma unroll
;           for (int ii = 0; ii < 16; ++ii) c += (key[blk * 16 + ii] >= cand) ? 1 : 0;
	v_ashrrev_i32_e32 v240, 31, v170
	v_or_b32_e32 v240, 0x80000000, v240
	v_xor_b32_e32 v240, v170, v240
	v_cmp_gt_i32_e64 s[68:69], s0, v0
	s_add_i32 s0, s15, 0xffffe5c1
	v_cndmask_b32_e64 v26, 0, v241, s[74:75]
	s_waitcnt vmcnt(22)
	v_ashrrev_i32_e32 v241, 31, v172
	v_or_b32_e32 v241, 0x80000000, v241
	v_xor_b32_e32 v241, v172, v241
	v_cmp_gt_i32_e64 s[70:71], s0, v0
	s_add_i32 s0, s15, 0xffffe581
	v_cndmask_b32_e64 v25, 0, v240, s[68:69]
	s_waitcnt vmcnt(21)
	v_ashrrev_i32_e32 v240, 31, v173
	v_or_b32_e32 v240, 0x80000000, v240
	v_xor_b32_e32 v240, v173, v240
	v_cmp_gt_i32_e64 s[72:73], s0, v0
	s_add_i32 s0, s15, 0xffffe541
	v_cndmask_b32_e64 v24, 0, v241, s[70:71]
	s_waitcnt vmcnt(20)
	v_ashrrev_i32_e32 v241, 31, v174
	v_or_b32_e32 v241, 0x80000000, v241
	v_xor_b32_e32 v241, v174, v241
	v_cmp_gt_i32_e64 s[74:75], s0, v0
	s_add_i32 s0, s15, 0xffffe501
	v_cndmask_b32_e64 v23, 0, v240, s[72:73]
	s_waitcnt vmcnt(19)
	v_ashrrev_i32_e32 v240, 31, v175
	v_or_b32_e32 v240, 0x80000000, v240
	v_xor_b32_e32 v240, v175, v240
	v_cmp_gt_i32_e64 s[68:69], s0, v0
	s_add_i32 s0, s15, 0xffffe4c1
	v_cndmask_b32_e64 v22, 0, v241, s[74:75]
	s_waitcnt vmcnt(18)
	v_ashrrev_i32_e32 v241, 31, v176
	v_or_b32_e32 v241, 0x80000000, v241
	v_xor_b32_e32 v241, v176, v241
	v_cmp_gt_i32_e64 s[70:71], s0, v0
	s_add_i32 s0, s15, 0xffffe481
	v_cndmask_b32_e64 v21, 0, v240, s[68:69]
	s_waitcnt vmcnt(17)
	v_ashrrev_i32_e32 v240, 31, v177
	v_or_b32_e32 v240, 0x80000000, v240
	v_xor_b32_e32 v240, v177, v240
	v_cmp_gt_i32_e64 s[72:73], s0, v0
	s_add_i32 s0, s15, 0xffffe441
	v_cndmask_b32_e64 v20, 0, v241, s[70:71]
	s_waitcnt vmcnt(16)
	v_ashrrev_i32_e32 v241, 31, v179
	v_or_b32_e32 v241, 0x80000000, v241
	v_xor_b32_e32 v241, v179, v241
	v_cmp_gt_i32_e64 s[74:75], s0, v0
	s_add_i32 s0, s15, 0xffffe401
	v_cndmask_b32_e64 v19, 0, v240, s[72:73]
	s_waitcnt vmcnt(15)
	v_ashrrev_i32_e32 v240, 31, v178
	v_or_b32_e32 v240, 0x80000000, v240
	v_xor_b32_e32 v240, v178, v240
	v_cmp_gt_i32_e64 s[68:69], s0, v0
	s_add_i32 s0, s15, 0xffffe3c1
	v_cndmask_b32_e64 v18, 0, v241, s[74:75]
	s_waitcnt vmcnt(14)
	v_ashrrev_i32_e32 v241, 31, v180
	v_or_b32_e32 v241, 0x80000000, v241
	v_xor_b32_e32 v241, v180, v241
	v_cmp_gt_i32_e64 s[70:71], s0, v0
	s_add_i32 s0, s15, 0xffffe381
	v_cndmask_b32_e64 v17, 0, v240, s[68:69]
	s_waitcnt vmcnt(13)
	v_ashrrev_i32_e32 v240, 31, v181
	v_or_b32_e32 v240, 0x80000000, v240
	v_xor_b32_e32 v240, v181, v240
	v_cmp_gt_i32_e64 s[72:73], s0, v0
	s_add_i32 s0, s15, 0xffffe341
	v_cndmask_b32_e64 v16, 0, v241, s[70:71]
	s_waitcnt vmcnt(12)
	v_ashrrev_i32_e32 v241, 31, v182
	v_or_b32_e32 v241, 0x80000000, v241
	v_xor_b32_e32 v241, v182, v241
	v_cmp_gt_i32_e64 s[74:75], s0, v0
	s_add_i32 s0, s15, 0xffffe301
	v_cndmask_b32_e64 v15, 0, v240, s[72:73]
	s_waitcnt vmcnt(11)
	v_ashrrev_i32_e32 v240, 31, v183
	v_or_b32_e32 v240, 0x80000000, v240
	v_xor_b32_e32 v240, v183, v240
	v_cmp_gt_i32_e64 s[68:69], s0, v0
	s_add_i32 s0, s15, 0xffffe2c1
	v_cndmask_b32_e64 v14, 0, v241, s[74:75]
	s_waitcnt vmcnt(10)
	v_ashrrev_i32_e32 v241, 31, v184
	v_or_b32_e32 v241, 0x80000000, v241
	v_xor_b32_e32 v241, v184, v241
	v_cmp_gt_i32_e64 s[70:71], s0, v0
	s_add_i32 s0, s15, 0xffffe281
	v_cndmask_b32_e64 v13, 0, v240, s[68:69]
	s_waitcnt vmcnt(9)
	v_ashrrev_i32_e32 v240, 31, v185
	v_or_b32_e32 v240, 0x80000000, v240
	v_xor_b32_e32 v240, v185, v240
	v_cmp_gt_i32_e64 s[72:73], s0, v0
	s_add_i32 s0, s15, 0xffffe241
	v_cndmask_b32_e64 v12, 0, v241, s[70:71]
	s_waitcnt vmcnt(8)
	v_ashrrev_i32_e32 v241, 31, v187
	v_or_b32_e32 v241, 0x80000000, v241
	v_xor_b32_e32 v241, v187, v241
	v_cmp_gt_i32_e64 s[74:75], s0, v0
	s_add_i32 s0, s15, 0xffffe201
	v_cndmask_b32_e64 v11, 0, v240, s[72:73]
	s_waitcnt vmcnt(7)
	v_ashrrev_i32_e32 v240, 31, v186
	v_or_b32_e32 v240, 0x80000000, v240
	v_xor_b32_e32 v240, v186, v240
	v_cmp_gt_i32_e64 s[68:69], s0, v0
	s_add_i32 s0, s15, 0xffffe1c1
	v_cndmask_b32_e64 v10, 0, v241, s[74:75]
	s_waitcnt vmcnt(6)
	v_ashrrev_i32_e32 v241, 31, v188
	v_or_b32_e32 v241, 0x80000000, v241
	v_xor_b32_e32 v241, v188, v241
	v_cmp_gt_i32_e64 s[70:71], s0, v0
	s_add_i32 s0, s15, 0xffffe181
	v_cndmask_b32_e64 v9, 0, v240, s[68:69]
	s_waitcnt vmcnt(5)
	v_ashrrev_i32_e32 v240, 31, v189
	v_or_b32_e32 v240, 0x80000000, v240
	v_xor_b32_e32 v240, v189, v240
	v_cmp_gt_i32_e64 s[72:73], s0, v0
	s_add_i32 s0, s15, 0xffffe141
	v_cndmask_b32_e64 v8, 0, v241, s[70:71]
	s_waitcnt vmcnt(4)
	v_ashrrev_i32_e32 v241, 31, v190
	v_or_b32_e32 v241, 0x80000000, v241
	v_xor_b32_e32 v241, v190, v241
	v_cmp_gt_i32_e64 s[74:75], s0, v0
	s_add_i32 s0, s15, 0xffffe101
	v_cndmask_b32_e64 v7, 0, v240, s[72:73]
	s_waitcnt vmcnt(3)
	v_ashrrev_i32_e32 v240, 31, v191
	v_or_b32_e32 v240, 0x80000000, v240
	v_xor_b32_e32 v240, v191, v240
	v_cmp_gt_i32_e64 s[68:69], s0, v0
	s_add_i32 s0, s15, 0xffffe0c1
	v_cndmask_b32_e64 v6, 0, v241, s[74:75]
	s_waitcnt vmcnt(2)
	v_ashrrev_i32_e32 v241, 31, v192
	v_or_b32_e32 v241, 0x80000000, v241
	v_xor_b32_e32 v241, v192, v241
	v_cmp_gt_i32_e64 s[70:71], s0, v0
	s_add_i32 s0, s15, 0xffffe081
	v_cndmask_b32_e64 v5, 0, v240, s[68:69]
	s_waitcnt vmcnt(1)
	v_ashrrev_i32_e32 v240, 31, v193
	v_or_b32_e32 v240, 0x80000000, v240
	v_xor_b32_e32 v240, v193, v240
	v_cmp_gt_i32_e64 s[72:73], s0, v0
	s_add_i32 s0, s15, 0xffffe041
	v_cndmask_b32_e64 v3, 0, v241, s[70:71]
	s_waitcnt vmcnt(0)
	v_ashrrev_i32_e32 v241, 31, v194
	v_or_b32_e32 v241, 0x80000000, v241
	v_xor_b32_e32 v241, v194, v241
	v_cmp_gt_i32_e64 s[74:75], s0, v0
	v_cndmask_b32_e64 v2, 0, v240, s[72:73]
	s_nop 1
	v_cndmask_b32_e64 v1, 0, v241, s[74:75]
	s_cmpk_gt_u32 s15, 0x3ff
	s_cselect_b64 s[0:1], -1, 0
	s_cmpk_gt_u32 s15, 0x7ff
	s_cselect_b64 s[52:53], -1, 0
	s_cmpk_gt_u32 s15, 0xbff
	s_cselect_b64 s[54:55], -1, 0
	s_cmpk_gt_u32 s15, 0xfff
	s_cselect_b64 s[56:57], -1, 0
	s_cmpk_gt_u32 s15, 0x13ff
	s_cselect_b64 s[58:59], -1, 0
	s_cmpk_gt_u32 s15, 0x17ff
	s_cselect_b64 s[60:61], -1, 0
	s_cmpk_gt_u32 s15, 0x1bff
	s_cselect_b64 s[62:63], -1, 0
	v_mov_b32_e32 v140, 31
	v_mov_b32_e32 v123, 0
	v_cndmask_b32_e64 v142, 0, 1, s[54:55]
	v_cmp_ne_u32_e64 s[64:65], 1, v142
	s_nop 3
	v_writelane_b32 v244, s64, 2
	v_writelane_b32 v244, s65, 3
	v_cndmask_b32_e64 v142, 0, 1, s[56:57]
	v_cmp_ne_u32_e64 s[64:65], 1, v142
	s_nop 3
	v_writelane_b32 v244, s64, 4
	v_writelane_b32 v244, s65, 5
	v_cndmask_b32_e64 v142, 0, 1, s[58:59]
	v_cmp_ne_u32_e64 s[64:65], 1, v142
	s_nop 3
	v_writelane_b32 v244, s64, 6
	v_writelane_b32 v244, s65, 7
	v_cndmask_b32_e64 v142, 0, 1, s[60:61]
	v_cmp_ne_u32_e64 s[64:65], 1, v142
	s_nop 3
	v_writelane_b32 v244, s64, 8
	v_writelane_b32 v244, s65, 9
	v_cndmask_b32_e64 v142, 0, 1, s[62:63]
	v_cmp_ne_u32_e64 s[64:65], 1, v142
	s_nop 3
	v_writelane_b32 v244, s64, 10
	v_writelane_b32 v244, s65, 11
	s_branch .LBB0_74
